# hgrn_prep: removed the full vmcnt(0) after the late v-row loads (hipcc's counted waits before the v stores already cover them)
# baseline (speedup 1.0000x reference)
; #define GAS __attribute__((address_space(1)))
; DI void hgrn_prep_job(const Frame& F, int job, int layer, LAS unsigned char* scr) {
;     ...
;     for (int half = 0; half < 2; ++half) {
;         const int dk = 64 * half + lane;
;         const float lb = ((const GAS float*)lbs)[dk];
;         const GAS bf16* pq = (const GAS bf16*)(P + m0 * NP + PB_Q + h * 128 + dk); const GAS bf16* pf = (const GAS bf16*)(P + m0 * NP + PB_F + h * 128 + dk); const GAS bf16* pv = (const GAS bf16*)(P + m0 * NP + PB_I + h * 128 + dk);
;         unsigned short ve[32];
; #pragma unroll
;         for (int t = 0; t < 32; ++t) ve[t] = pv[(size_t)t * NP];
;         float bq[32], kv[32], qv[32]; float bsum = 0.f;
;         unsigned short qe[32], fe[32];
; #pragma unroll
;         for (int t = 0; t < 32; ++t) { qe[t] = pq[(size_t)t * NP]; fe[t] = pf[(size_t)t * NP]; }
.LBB0_810:
	v_or_b32_e32 v96, s0, v48
	v_lshlrev_b64 v[6:7], 1, v[96:97]
	v_lshl_add_u64 v[8:9], s[70:71], 0, v[6:7]
	v_lshl_add_u64 v[14:15], s[66:67], 0, v[6:7]
	v_lshl_add_u64 v[12:13], s[68:69], 0, v[6:7]
	v_mov_b32_e32 v139, v6
	global_load_ushort v141, v139, s[66:67] offset:3072
	global_load_ushort v173, v139, s[68:69]
	v_add_u32_e32 v140, 0x3c00, v139
	global_load_ushort v142, v140, s[66:67] offset:3072
	global_load_ushort v174, v140, s[68:69]
	v_add_u32_e32 v140, 0x7800, v139
	global_load_ushort v143, v140, s[66:67] offset:3072
	global_load_ushort v175, v140, s[68:69]
	v_add_u32_e32 v140, 0xb400, v139
	global_load_ushort v144, v140, s[66:67] offset:3072
	global_load_ushort v176, v140, s[68:69]
	v_add_u32_e32 v140, 0xf000, v139
	global_load_ushort v145, v140, s[66:67] offset:3072
	global_load_ushort v177, v140, s[68:69]
	v_add_u32_e32 v140, 0x12c00, v139
	global_load_ushort v146, v140, s[66:67] offset:3072
	global_load_ushort v178, v140, s[68:69]
	v_add_u32_e32 v140, 0x16800, v139
	global_load_ushort v147, v140, s[66:67] offset:3072
	global_load_ushort v179, v140, s[68:69]
	v_add_u32_e32 v140, 0x1a400, v139
	global_load_ushort v148, v140, s[66:67] offset:3072
	global_load_ushort v180, v140, s[68:69]
	v_add_u32_e32 v140, 0x1e000, v139
	global_load_ushort v149, v140, s[66:67] offset:3072
	global_load_ushort v181, v140, s[68:69]
	v_add_u32_e32 v140, 0x21c00, v139
	global_load_ushort v150, v140, s[66:67] offset:3072
	global_load_ushort v182, v140, s[68:69]
	v_add_u32_e32 v140, 0x25800, v139
	global_load_ushort v151, v140, s[66:67] offset:3072
	global_load_ushort v183, v140, s[68:69]
	v_add_u32_e32 v140, 0x29400, v139
	global_load_ushort v152, v140, s[66:67] offset:3072
	global_load_ushort v186, v140, s[68:69]
	v_add_u32_e32 v140, 0x2d000, v139
	global_load_ushort v153, v140, s[66:67] offset:3072
	global_load_ushort v187, v140, s[68:69]
	v_add_u32_e32 v140, 0x30c00, v139
	global_load_ushort v154, v140, s[66:67] offset:3072
	global_load_ushort v188, v140, s[68:69]
	v_add_u32_e32 v140, 0x34800, v139
	global_load_ushort v155, v140, s[66:67] offset:3072
	global_load_ushort v189, v140, s[68:69]
	v_add_u32_e32 v140, 0x38400, v139
	global_load_ushort v156, v140, s[66:67] offset:3072
	global_load_ushort v190, v140, s[68:69]
	v_add_u32_e32 v140, 0x3c000, v139
	global_load_ushort v157, v140, s[66:67] offset:3072
	global_load_ushort v191, v140, s[68:69]
	v_add_u32_e32 v140, 0x3fc00, v139
	global_load_ushort v158, v140, s[66:67] offset:3072
	global_load_ushort v192, v140, s[68:69]
	v_add_u32_e32 v140, 0x43800, v139
	global_load_ushort v159, v140, s[66:67] offset:3072
	global_load_ushort v193, v140, s[68:69]
	v_add_u32_e32 v140, 0x47400, v139
	global_load_ushort v160, v140, s[66:67] offset:3072
	global_load_ushort v194, v140, s[68:69]
	v_add_u32_e32 v140, 0x4b000, v139
	global_load_ushort v161, v140, s[66:67] offset:3072
	global_load_ushort v195, v140, s[68:69]
	v_add_u32_e32 v140, 0x4ec00, v139
	global_load_ushort v162, v140, s[66:67] offset:3072
	global_load_ushort v196, v140, s[68:69]
	v_add_u32_e32 v140, 0x52800, v139
	global_load_ushort v163, v140, s[66:67] offset:3072
	global_load_ushort v197, v140, s[68:69]
	v_add_u32_e32 v140, 0x56400, v139
	global_load_ushort v164, v140, s[66:67] offset:3072
	global_load_ushort v198, v140, s[68:69]
	v_add_u32_e32 v140, 0x5a000, v139
	global_load_ushort v165, v140, s[66:67] offset:3072
	global_load_ushort v199, v140, s[68:69]
	v_add_u32_e32 v140, 0x5dc00, v139
	global_load_ushort v166, v140, s[66:67] offset:3072
	global_load_ushort v200, v140, s[68:69]
	v_add_u32_e32 v140, 0x61800, v139
	global_load_ushort v167, v140, s[66:67] offset:3072
	global_load_ushort v201, v140, s[68:69]
	v_add_u32_e32 v140, 0x65400, v139
	global_load_ushort v168, v140, s[66:67] offset:3072
	global_load_ushort v202, v140, s[68:69]
	v_add_u32_e32 v140, 0x69000, v139
	global_load_ushort v169, v140, s[66:67] offset:3072
	global_load_ushort v203, v140, s[68:69]
	v_add_u32_e32 v140, 0x6cc00, v139
	global_load_ushort v170, v140, s[66:67] offset:3072
	global_load_ushort v204, v140, s[68:69]
	v_add_u32_e32 v140, 0x70800, v139
	global_load_ushort v171, v140, s[66:67] offset:3072
	global_load_ushort v205, v140, s[68:69]
	v_add_u32_e32 v140, 0x74400, v139
	global_load_ushort v172, v140, s[66:67] offset:3072
	global_load_ushort v206, v140, s[68:69]
	v_add_co_u32_e32 v6, vcc, 0x7000, v8
	v_lshlrev_b64 v[10:11], 2, v[96:97]
	s_nop 0
	v_addc_co_u32_e32 v7, vcc, 0, v9, vcc
	global_load_ushort v59, v[6:7], off offset:2048
	v_add_co_u32_e32 v6, vcc, 0xf000, v8
	v_lshl_add_u64 v[4:5], s[56:57], 0, v[10:11]
	s_nop 0
	v_addc_co_u32_e32 v7, vcc, 0, v9, vcc
	global_load_dword v4, v[4:5], off
	s_movk_i32 s0, 0x7000
	global_load_ushort v58, v[8:9], off
	global_load_ushort v60, v[6:7], off
	v_add_co_u32_e32 v6, vcc, s74, v8
	s_nop 0
	v_addc_co_u32_e32 v7, vcc, 0, v9, vcc
	global_load_ushort v61, v[6:7], off offset:2048
	v_add_co_u32_e32 v6, vcc, s89, v8
	v_lshl_add_u32 v119, v96, 1, s31
	s_nop 0
	v_addc_co_u32_e32 v7, vcc, 0, v9, vcc
	global_load_ushort v62, v[6:7], off
	v_add_co_u32_e32 v6, vcc, 0x25000, v8
	s_waitcnt vmcnt(2)
	s_waitcnt vmcnt(0)
; DI float bf2f(unsigned v) { return __uint_as_float(v << 16); }
; DI float flog(float x) { return __builtin_amdgcn_logf(x) * 0.6931471805599453f; }
; DI float sigm(float x) { return frcp(1.f + fexp(-x)); }
; DI float silu(float x) { return x * sigm(x); }
; DI void hgrn_prep_job(const Frame& F, int job, int layer, LAS unsigned char* scr) {
;     ...
;         for (int t = 0; t < 32; ++t) { qe[t] = pq[(size_t)t * NP]; fe[t] = pf[(size_t)t * NP]; }
; #pragma unroll
;         for (int t = 0; t < 32; ++t) {
;             const float qx = bf2f(qe[t]), fx = bf2f(fe[t]);
;             const float f = lb + (1.f - lb) * sigm(fx);
;             bsum += flog(f); bq[t] = bsum; kv[t] = 1.f - f; qv[t] = silu(qx);
	v_lshlrev_b32_e32 v5, 16, v141
	v_addc_co_u32_e32 v7, vcc, 0, v9, vcc
	global_load_ushort v63, v[6:7], off offset:2048
	v_add_co_u32_e32 v6, vcc, 0x2d000, v8
	s_nop 1
	v_addc_co_u32_e32 v7, vcc, 0, v9, vcc
	global_load_ushort v64, v[6:7], off
	v_add_co_u32_e32 v6, vcc, 0x34000, v8
	s_nop 1
	v_addc_co_u32_e32 v7, vcc, 0, v9, vcc
	global_load_ushort v65, v[6:7], off offset:2048
	v_add_co_u32_e32 v6, vcc, 0x3c000, v8
	s_nop 1
	v_addc_co_u32_e32 v7, vcc, 0, v9, vcc
	global_load_ushort v66, v[6:7], off
	v_add_co_u32_e32 v6, vcc, 0x43000, v8
	s_nop 1
	v_addc_co_u32_e32 v7, vcc, 0, v9, vcc
	global_load_ushort v67, v[6:7], off offset:2048
	v_add_co_u32_e32 v6, vcc, 0x4b000, v8
	s_nop 1
	v_addc_co_u32_e32 v7, vcc, 0, v9, vcc
	global_load_ushort v68, v[6:7], off
	v_add_co_u32_e32 v6, vcc, 0x52000, v8
	s_nop 1
	v_addc_co_u32_e32 v7, vcc, 0, v9, vcc
	global_load_ushort v69, v[6:7], off offset:2048
	v_add_co_u32_e32 v6, vcc, 0x5a000, v8
	s_nop 1
	v_addc_co_u32_e32 v7, vcc, 0, v9, vcc
	global_load_ushort v70, v[6:7], off
	v_add_co_u32_e32 v6, vcc, 0x61000, v8
	s_nop 1
	v_addc_co_u32_e32 v7, vcc, 0, v9, vcc
	global_load_ushort v71, v[6:7], off offset:2048
	v_add_co_u32_e32 v6, vcc, 0x69000, v8
	s_nop 1
	v_addc_co_u32_e32 v7, vcc, 0, v9, vcc
	global_load_ushort v72, v[6:7], off
	v_add_co_u32_e32 v6, vcc, 0x70000, v8
	s_nop 1
	v_addc_co_u32_e32 v7, vcc, 0, v9, vcc
	global_load_ushort v73, v[6:7], off offset:2048
	v_add_co_u32_e32 v18, vcc, s4, v14
	s_nop 0
	v_addc_co_u32_e32 v19, vcc, 0, v15, vcc
	v_sub_f32_e32 v6, 1.0, v4
	v_lshlrev_b32_e32 v7, 16, v173
	v_mul_f32_e32 v7, 0xbfb8aa3b, v7
	v_exp_f32_e32 v7, v7
	s_nop 0
	v_add_f32_e32 v7, 1.0, v7
	v_rcp_f32_e32 v16, v7
	v_mul_f32_e32 v7, 0xbfb8aa3b, v5
	v_exp_f32_e32 v7, v7
	s_nop 0
	v_add_f32_e32 v7, 1.0, v7
	v_rcp_f32_e32 v7, v7
	s_nop 0
	v_mul_f32_e32 v7, v7, v5
	v_add_co_u32_e32 v18, vcc, s14, v12
	v_lshlrev_b32_e32 v5, 16, v142
	v_addc_co_u32_e32 v19, vcc, 0, v13, vcc
	v_mul_f32_e32 v18, 0xbfb8aa3b, v5
	v_exp_f32_e32 v18, v18
	v_lshlrev_b32_e32 v17, 16, v174
	v_add_f32_e32 v18, 1.0, v18
	v_rcp_f32_e32 v18, v18
	v_mul_f32_e32 v17, 0xbfb8aa3b, v17
	v_exp_f32_e32 v17, v17
	v_mul_f32_e32 v5, v18, v5
	v_add_co_u32_e32 v18, vcc, s88, v14
	v_add_f32_e32 v17, 1.0, v17
	s_nop 0
	v_addc_co_u32_e32 v19, vcc, 0, v15, vcc
	v_rcp_f32_e32 v17, v17
	v_lshlrev_b32_e32 v20, 16, v143
	v_add_co_u32_e32 v18, vcc, s0, v12
	s_mov_b32 s0, 0xc000
	s_nop 0
	v_addc_co_u32_e32 v19, vcc, 0, v13, vcc
	v_lshlrev_b32_e32 v18, 16, v175
	v_mul_f32_e32 v18, 0xbfb8aa3b, v18
	v_exp_f32_e32 v18, v18
	s_nop 0
	v_add_f32_e32 v18, 1.0, v18
	v_rcp_f32_e32 v24, v18
	v_mul_f32_e32 v18, 0xbfb8aa3b, v20
	v_exp_f32_e32 v18, v18
	s_nop 0
	v_add_f32_e32 v18, 1.0, v18
	v_rcp_f32_e32 v18, v18
	s_nop 0
	v_mul_f32_e32 v74, v18, v20
	v_add_co_u32_e32 v18, vcc, s0, v14
	s_mov_b32 s0, 0x13000
	s_nop 0
	v_addc_co_u32_e32 v19, vcc, 0, v15, vcc
	v_lshlrev_b32_e32 v20, 16, v144
	v_add_co_u32_e32 v18, vcc, s15, v12
	s_nop 1
	v_addc_co_u32_e32 v19, vcc, 0, v13, vcc
	v_lshlrev_b32_e32 v18, 16, v176
	v_mul_f32_e32 v18, 0xbfb8aa3b, v18
	v_exp_f32_e32 v18, v18
	s_nop 0
	v_add_f32_e32 v18, 1.0, v18
	v_rcp_f32_e32 v25, v18
	v_mul_f32_e32 v18, 0xbfb8aa3b, v20
	v_exp_f32_e32 v18, v18
	s_nop 0
	v_add_f32_e32 v18, 1.0, v18
	v_rcp_f32_e32 v18, v18
	s_nop 0
	v_mul_f32_e32 v76, v18, v20
	v_add_co_u32_e32 v18, vcc, s8, v14
	s_nop 1
	v_addc_co_u32_e32 v19, vcc, 0, v15, vcc
	v_lshlrev_b32_e32 v20, 16, v145
	v_add_co_u32_e32 v18, vcc, s8, v12
	s_nop 1
	v_addc_co_u32_e32 v19, vcc, 0, v13, vcc
	v_mul_f32_e32 v19, 0xbfb8aa3b, v20
	v_exp_f32_e32 v19, v19
	v_lshlrev_b32_e32 v18, 16, v177
	v_add_f32_e32 v19, 1.0, v19
	v_rcp_f32_e32 v19, v19
	v_mul_f32_e32 v18, 0xbfb8aa3b, v18
	v_exp_f32_e32 v18, v18
	v_mul_f32_e32 v75, v19, v20
	v_add_co_u32_e32 v20, vcc, s0, v14
	s_mov_b32 s0, 0x17000
	s_nop 0
	v_addc_co_u32_e32 v21, vcc, 0, v15, vcc
	v_add_co_u32_e32 v20, vcc, s37, v12
	v_add_f32_e32 v18, 1.0, v18
	s_nop 0
	v_addc_co_u32_e32 v21, vcc, 0, v13, vcc
	v_rcp_f32_e32 v18, v18
	v_lshlrev_b32_e32 v22, 16, v146
	v_mul_f32_e32 v20, 0xbfb8aa3b, v22
	v_exp_f32_e32 v20, v20
	v_lshlrev_b32_e32 v19, 16, v178
	v_add_f32_e32 v20, 1.0, v20
	v_rcp_f32_e32 v20, v20
	v_mul_f32_e32 v19, 0xbfb8aa3b, v19
	v_exp_f32_e32 v19, v19
	v_mul_f32_e32 v77, v20, v22
	v_add_co_u32_e32 v20, vcc, s0, v14
	s_mov_b32 s0, 0x1b000
	s_nop 0
	v_addc_co_u32_e32 v21, vcc, 0, v15, vcc
	v_add_f32_e32 v19, 1.0, v19
	v_rcp_f32_e32 v19, v19
	v_lshlrev_b32_e32 v23, 16, v147
	v_add_co_u32_e32 v20, vcc, s74, v12
	s_nop 1
	v_addc_co_u32_e32 v21, vcc, 0, v13, vcc
	v_lshlrev_b32_e32 v20, 16, v179
	v_mul_f32_e32 v20, 0xbfb8aa3b, v20
	v_exp_f32_e32 v20, v20
	s_nop 0
	v_add_f32_e32 v20, 1.0, v20
	v_rcp_f32_e32 v22, v20
	v_mul_f32_e32 v20, 0xbfb8aa3b, v23
	v_exp_f32_e32 v20, v20
	s_nop 0
	v_add_f32_e32 v20, 1.0, v20
	v_rcp_f32_e32 v20, v20
	s_nop 0
	v_mul_f32_e32 v91, v20, v23
	v_add_co_u32_e32 v20, vcc, s0, v14
	s_mov_b32 s0, 0x25000
	s_nop 0
	v_addc_co_u32_e32 v21, vcc, 0, v15, vcc
	v_lshlrev_b32_e32 v26, 16, v148
	v_add_co_u32_e32 v20, vcc, s5, v12
	s_nop 1
	v_addc_co_u32_e32 v21, vcc, 0, v13, vcc
	v_lshlrev_b32_e32 v20, 16, v180
	v_mul_f32_e32 v20, 0xbfb8aa3b, v20
	v_exp_f32_e32 v20, v20
	s_nop 0
	v_add_f32_e32 v20, 1.0, v20
	v_rcp_f32_e32 v23, v20
	v_mul_f32_e32 v20, 0xbfb8aa3b, v26
	v_exp_f32_e32 v20, v20
	s_nop 0
	v_add_f32_e32 v20, 1.0, v20
	v_rcp_f32_e32 v20, v20
	s_nop 0
	v_mul_f32_e32 v99, v20, v26
	v_add_co_u32_e32 v20, vcc, s89, v14
	s_nop 1
	v_addc_co_u32_e32 v21, vcc, 0, v15, vcc
	v_lshlrev_b32_e32 v26, 16, v149
	v_add_co_u32_e32 v20, vcc, s89, v12
	s_nop 1
	v_addc_co_u32_e32 v21, vcc, 0, v13, vcc
	v_mul_f32_e32 v21, 0xbfb8aa3b, v26
; DI float bf2f(unsigned v) { return __uint_as_float(v << 16); }
; DI float flog(float x) { return __builtin_amdgcn_logf(x) * 0.6931471805599453f; }
; DI float sigm(float x) { return frcp(1.f + fexp(-x)); }
; DI float silu(float x) { return x * sigm(x); }
; DI void hgrn_prep_job(const Frame& F, int job, int layer, LAS unsigned char* scr) {
;     ...
;         for (int t = 0; t < 32; ++t) { qe[t] = pq[(size_t)t * NP]; fe[t] = pf[(size_t)t * NP]; }
; #pragma unroll
;         for (int t = 0; t < 32; ++t) {
;             const float qx = bf2f(qe[t]), fx = bf2f(fe[t]);
;             const float f = lb + (1.f - lb) * sigm(fx);
;             bsum += flog(f); bq[t] = bsum; kv[t] = 1.f - f; qv[t] = silu(qx);
	v_exp_f32_e32 v21, v21
	v_lshlrev_b32_e32 v20, 16, v181
	v_add_f32_e32 v21, 1.0, v21
	v_rcp_f32_e32 v21, v21
	v_mul_f32_e32 v20, 0xbfb8aa3b, v20
	v_exp_f32_e32 v20, v20
	v_mul_f32_e32 v95, v21, v26
	v_add_co_u32_e32 v26, vcc, s16, v14
	v_add_f32_e32 v20, 1.0, v20
	s_nop 0
	v_addc_co_u32_e32 v27, vcc, 0, v15, vcc
	v_add_co_u32_e32 v26, vcc, s17, v12
	v_rcp_f32_e32 v20, v20
	s_nop 0
	v_addc_co_u32_e32 v27, vcc, 0, v13, vcc
	v_lshlrev_b32_e32 v28, 16, v150
	v_mul_f32_e32 v26, 0xbfb8aa3b, v28
	v_exp_f32_e32 v26, v26
	v_lshlrev_b32_e32 v21, 16, v182
	v_add_f32_e32 v26, 1.0, v26
	v_rcp_f32_e32 v26, v26
	v_mul_f32_e32 v21, 0xbfb8aa3b, v21
	v_exp_f32_e32 v21, v21
	v_mul_f32_e32 v98, v26, v28
	v_add_co_u32_e32 v26, vcc, s6, v14
	v_add_f32_e32 v21, 1.0, v21
	s_nop 0
	v_addc_co_u32_e32 v27, vcc, 0, v15, vcc
	v_rcp_f32_e32 v21, v21
	v_lshlrev_b32_e32 v29, 16, v151
	v_add_co_u32_e32 v26, vcc, s0, v12
	s_mov_b32 s0, 0x2a000
	s_nop 0
	v_addc_co_u32_e32 v27, vcc, 0, v13, vcc
	v_lshlrev_b32_e32 v26, 16, v183
	v_mul_f32_e32 v26, 0xbfb8aa3b, v26
	v_exp_f32_e32 v26, v26
	s_nop 0
	v_add_f32_e32 v26, 1.0, v26
	v_rcp_f32_e32 v28, v26
	v_mul_f32_e32 v26, 0xbfb8aa3b, v29
	v_exp_f32_e32 v26, v26
	s_nop 0
	v_add_f32_e32 v26, 1.0, v26
	v_rcp_f32_e32 v26, v26
	s_nop 0
	v_mul_f32_e32 v101, v26, v29
	v_add_co_u32_e32 v26, vcc, s0, v14
	s_mov_b32 s0, 0x31000
	s_nop 0
	v_addc_co_u32_e32 v27, vcc, 0, v15, vcc
	v_lshlrev_b32_e32 v30, 16, v152
	v_add_co_u32_e32 v26, vcc, s18, v12
	s_nop 1
	v_addc_co_u32_e32 v27, vcc, 0, v13, vcc
	v_lshlrev_b32_e32 v26, 16, v186
	v_mul_f32_e32 v26, 0xbfb8aa3b, v26
	v_exp_f32_e32 v26, v26
	s_nop 0
	v_add_f32_e32 v26, 1.0, v26
	v_rcp_f32_e32 v29, v26
	v_mul_f32_e32 v26, 0xbfb8aa3b, v30
	v_exp_f32_e32 v26, v26
	s_nop 0
	v_add_f32_e32 v26, 1.0, v26
	v_rcp_f32_e32 v26, v26
	s_nop 0
	v_mul_f32_e32 v103, v26, v30
	v_add_co_u32_e32 v26, vcc, s9, v14
	s_nop 1
	v_addc_co_u32_e32 v27, vcc, 0, v15, vcc
	v_lshlrev_b32_e32 v30, 16, v153
	v_add_co_u32_e32 v26, vcc, s9, v12
	s_nop 1
	v_addc_co_u32_e32 v27, vcc, 0, v13, vcc
	v_mul_f32_e32 v27, 0xbfb8aa3b, v30
	v_exp_f32_e32 v27, v27
	v_lshlrev_b32_e32 v26, 16, v187
	v_add_f32_e32 v27, 1.0, v27
	v_rcp_f32_e32 v27, v27
	v_mul_f32_e32 v26, 0xbfb8aa3b, v26
	v_exp_f32_e32 v26, v26
	v_mul_f32_e32 v102, v27, v30
	v_add_co_u32_e32 v30, vcc, s0, v14
	s_mov_b32 s0, 0x35000
	s_nop 0
	v_addc_co_u32_e32 v31, vcc, 0, v15, vcc
	v_add_co_u32_e32 v30, vcc, s96, v12
	v_add_f32_e32 v26, 1.0, v26
	s_nop 0
	v_addc_co_u32_e32 v31, vcc, 0, v13, vcc
	v_rcp_f32_e32 v26, v26
	v_lshlrev_b32_e32 v32, 16, v154
	v_mul_f32_e32 v30, 0xbfb8aa3b, v32
	v_exp_f32_e32 v30, v30
	v_lshlrev_b32_e32 v27, 16, v188
	v_add_f32_e32 v30, 1.0, v30
	v_rcp_f32_e32 v30, v30
	v_mul_f32_e32 v27, 0xbfb8aa3b, v27
	v_exp_f32_e32 v27, v27
	v_mul_f32_e32 v104, v30, v32
	v_add_co_u32_e32 v30, vcc, s0, v14
	s_mov_b32 s0, 0x34000
	s_nop 0
	v_addc_co_u32_e32 v31, vcc, 0, v15, vcc
	v_add_f32_e32 v27, 1.0, v27
	v_rcp_f32_e32 v27, v27
	v_lshlrev_b32_e32 v32, 16, v155
	v_add_co_u32_e32 v30, vcc, s0, v12
	s_mov_b32 s0, 0x39000
	s_nop 0
	v_addc_co_u32_e32 v31, vcc, 0, v13, vcc
	v_mul_f32_e32 v31, 0xbfb8aa3b, v32
	v_exp_f32_e32 v31, v31
	v_lshlrev_b32_e32 v30, 16, v189
	v_add_f32_e32 v31, 1.0, v31
	v_rcp_f32_e32 v31, v31
	v_mul_f32_e32 v30, 0xbfb8aa3b, v30
	v_exp_f32_e32 v30, v30
	v_mul_f32_e32 v105, v31, v32
	v_add_co_u32_e32 v32, vcc, s0, v14
	s_mov_b32 s0, 0x40000
	s_nop 0
	v_addc_co_u32_e32 v33, vcc, 0, v15, vcc
	v_add_co_u32_e32 v32, vcc, s19, v12
	v_add_f32_e32 v30, 1.0, v30
	s_nop 0
	v_addc_co_u32_e32 v33, vcc, 0, v13, vcc
	v_rcp_f32_e32 v30, v30
	v_lshlrev_b32_e32 v34, 16, v156
	v_mul_f32_e32 v32, 0xbfb8aa3b, v34
	v_exp_f32_e32 v32, v32
	v_lshlrev_b32_e32 v31, 16, v190
	v_add_f32_e32 v32, 1.0, v32
	v_rcp_f32_e32 v32, v32
	v_mul_f32_e32 v31, 0xbfb8aa3b, v31
	v_exp_f32_e32 v31, v31
	v_mul_f32_e32 v106, v32, v34
	v_add_co_u32_e32 v32, vcc, s10, v14
	v_add_f32_e32 v31, 1.0, v31
	s_nop 0
	v_addc_co_u32_e32 v33, vcc, 0, v15, vcc
	v_rcp_f32_e32 v31, v31
	v_lshlrev_b32_e32 v34, 16, v157
	v_add_co_u32_e32 v32, vcc, s10, v12
	s_nop 1
	v_addc_co_u32_e32 v33, vcc, 0, v13, vcc
	v_mul_f32_e32 v33, 0xbfb8aa3b, v34
	v_exp_f32_e32 v33, v33
	v_lshlrev_b32_e32 v32, 16, v191
	v_add_f32_e32 v33, 1.0, v33
	v_rcp_f32_e32 v33, v33
	v_mul_f32_e32 v32, 0xbfb8aa3b, v32
	v_exp_f32_e32 v32, v32
	v_mul_f32_e32 v107, v33, v34
	v_add_co_u32_e32 v34, vcc, s0, v14
	s_mov_b32 s0, 0x44000
	s_nop 0
	v_addc_co_u32_e32 v35, vcc, 0, v15, vcc
	v_add_co_u32_e32 v34, vcc, s20, v12
	v_add_f32_e32 v32, 1.0, v32
	s_nop 0
	v_addc_co_u32_e32 v35, vcc, 0, v13, vcc
	v_rcp_f32_e32 v32, v32
	v_lshlrev_b32_e32 v36, 16, v158
	v_mul_f32_e32 v34, 0xbfb8aa3b, v36
	v_exp_f32_e32 v34, v34
	v_lshlrev_b32_e32 v33, 16, v192
	v_add_f32_e32 v34, 1.0, v34
	v_rcp_f32_e32 v34, v34
	v_mul_f32_e32 v33, 0xbfb8aa3b, v33
	v_exp_f32_e32 v33, v33
	v_mul_f32_e32 v108, v34, v36
	v_add_co_u32_e32 v34, vcc, s0, v14
	s_mov_b32 s0, 0x43000
	s_nop 0
	v_addc_co_u32_e32 v35, vcc, 0, v15, vcc
	v_add_f32_e32 v33, 1.0, v33
	v_rcp_f32_e32 v33, v33
	v_lshlrev_b32_e32 v37, 16, v159
	v_add_co_u32_e32 v34, vcc, s0, v12
	s_mov_b32 s0, 0x48000
	s_nop 0
	v_addc_co_u32_e32 v35, vcc, 0, v13, vcc
	v_lshlrev_b32_e32 v34, 16, v193
	v_mul_f32_e32 v34, 0xbfb8aa3b, v34
	v_exp_f32_e32 v34, v34
	s_nop 0
	v_add_f32_e32 v34, 1.0, v34
	v_rcp_f32_e32 v36, v34
	v_mul_f32_e32 v34, 0xbfb8aa3b, v37
	v_exp_f32_e32 v34, v34
	s_nop 0
	v_add_f32_e32 v34, 1.0, v34
	v_rcp_f32_e32 v34, v34
	s_nop 0
	v_mul_f32_e32 v109, v34, v37
	v_add_co_u32_e32 v34, vcc, s0, v14
	s_mov_b32 s0, 0x4f000
	s_nop 0
	v_addc_co_u32_e32 v35, vcc, 0, v15, vcc
	v_lshlrev_b32_e32 v38, 16, v160
; DI float bf2f(unsigned v) { return __uint_as_float(v << 16); }
; DI float flog(float x) { return __builtin_amdgcn_logf(x) * 0.6931471805599453f; }
; DI float sigm(float x) { return frcp(1.f + fexp(-x)); }
; DI float silu(float x) { return x * sigm(x); }
; DI void hgrn_prep_job(const Frame& F, int job, int layer, LAS unsigned char* scr) {
;     ...
;         for (int t = 0; t < 32; ++t) { qe[t] = pq[(size_t)t * NP]; fe[t] = pf[(size_t)t * NP]; }
; #pragma unroll
;         for (int t = 0; t < 32; ++t) {
;             const float qx = bf2f(qe[t]), fx = bf2f(fe[t]);
;             const float f = lb + (1.f - lb) * sigm(fx);
;             bsum += flog(f); bq[t] = bsum; kv[t] = 1.f - f; qv[t] = silu(qx);
	v_add_co_u32_e32 v34, vcc, s21, v12
	s_nop 1
	v_addc_co_u32_e32 v35, vcc, 0, v13, vcc
	v_lshlrev_b32_e32 v34, 16, v194
	v_mul_f32_e32 v34, 0xbfb8aa3b, v34
	v_exp_f32_e32 v34, v34
	s_nop 0
	v_add_f32_e32 v34, 1.0, v34
	v_rcp_f32_e32 v37, v34
	v_mul_f32_e32 v34, 0xbfb8aa3b, v38
	v_exp_f32_e32 v34, v34
	s_nop 0
	v_add_f32_e32 v34, 1.0, v34
	v_rcp_f32_e32 v34, v34
	s_nop 0
	v_mul_f32_e32 v110, v34, v38
	v_add_co_u32_e32 v34, vcc, s11, v14
	s_nop 1
	v_addc_co_u32_e32 v35, vcc, 0, v15, vcc
	v_lshlrev_b32_e32 v38, 16, v161
	v_add_co_u32_e32 v34, vcc, s11, v12
	s_nop 1
	v_addc_co_u32_e32 v35, vcc, 0, v13, vcc
	v_mul_f32_e32 v35, 0xbfb8aa3b, v38
	v_exp_f32_e32 v35, v35
	v_lshlrev_b32_e32 v34, 16, v195
	v_add_f32_e32 v35, 1.0, v35
	v_rcp_f32_e32 v35, v35
	v_mul_f32_e32 v34, 0xbfb8aa3b, v34
	v_exp_f32_e32 v34, v34
	v_mul_f32_e32 v111, v35, v38
	v_add_co_u32_e32 v38, vcc, s0, v14
	s_mov_b32 s0, 0x53000
	s_nop 0
	v_addc_co_u32_e32 v39, vcc, 0, v15, vcc
	v_add_co_u32_e32 v38, vcc, s22, v12
	v_add_f32_e32 v34, 1.0, v34
	s_nop 0
	v_addc_co_u32_e32 v39, vcc, 0, v13, vcc
	v_rcp_f32_e32 v34, v34
	v_lshlrev_b32_e32 v40, 16, v162
	v_mul_f32_e32 v38, 0xbfb8aa3b, v40
	v_exp_f32_e32 v38, v38
	v_lshlrev_b32_e32 v35, 16, v196
	v_add_f32_e32 v38, 1.0, v38
	v_rcp_f32_e32 v38, v38
	v_mul_f32_e32 v35, 0xbfb8aa3b, v35
	v_exp_f32_e32 v35, v35
	v_mul_f32_e32 v112, v38, v40
	v_add_co_u32_e32 v38, vcc, s0, v14
	s_mov_b32 s0, 0x52000
	s_nop 0
	v_addc_co_u32_e32 v39, vcc, 0, v15, vcc
	v_add_f32_e32 v35, 1.0, v35
	v_rcp_f32_e32 v35, v35
	v_lshlrev_b32_e32 v41, 16, v163
	v_add_co_u32_e32 v38, vcc, s0, v12
	s_mov_b32 s0, 0x57000
	s_nop 0
	v_addc_co_u32_e32 v39, vcc, 0, v13, vcc
	v_lshlrev_b32_e32 v38, 16, v197
	v_mul_f32_e32 v38, 0xbfb8aa3b, v38
	v_exp_f32_e32 v38, v38
	s_nop 0
	v_add_f32_e32 v38, 1.0, v38
	v_rcp_f32_e32 v40, v38
	v_mul_f32_e32 v38, 0xbfb8aa3b, v41
	v_exp_f32_e32 v38, v38
	s_nop 0
	v_add_f32_e32 v38, 1.0, v38
	v_rcp_f32_e32 v38, v38
	s_nop 0
	v_mul_f32_e32 v113, v38, v41
	v_add_co_u32_e32 v38, vcc, s0, v14
	s_mov_b32 s0, 0x5e000
	s_nop 0
	v_addc_co_u32_e32 v39, vcc, 0, v15, vcc
	v_lshlrev_b32_e32 v42, 16, v164
	v_add_co_u32_e32 v38, vcc, s23, v12
	s_nop 1
	v_addc_co_u32_e32 v39, vcc, 0, v13, vcc
	v_lshlrev_b32_e32 v38, 16, v198
	v_mul_f32_e32 v38, 0xbfb8aa3b, v38
	v_exp_f32_e32 v38, v38
	s_nop 0
	v_add_f32_e32 v38, 1.0, v38
	v_rcp_f32_e32 v41, v38
	v_mul_f32_e32 v38, 0xbfb8aa3b, v42
	v_exp_f32_e32 v38, v38
	s_nop 0
	v_add_f32_e32 v38, 1.0, v38
	v_rcp_f32_e32 v38, v38
	s_nop 0
	v_mul_f32_e32 v114, v38, v42
	v_add_co_u32_e32 v38, vcc, s12, v14
	s_nop 1
	v_addc_co_u32_e32 v39, vcc, 0, v15, vcc
	v_lshlrev_b32_e32 v42, 16, v165
	v_add_co_u32_e32 v38, vcc, s12, v12
	s_nop 1
	v_addc_co_u32_e32 v39, vcc, 0, v13, vcc
	v_mul_f32_e32 v39, 0xbfb8aa3b, v42
	v_exp_f32_e32 v39, v39
	v_lshlrev_b32_e32 v38, 16, v199
	v_add_f32_e32 v39, 1.0, v39
	v_rcp_f32_e32 v39, v39
	v_mul_f32_e32 v38, 0xbfb8aa3b, v38
	v_exp_f32_e32 v38, v38
	v_mul_f32_e32 v115, v39, v42
	v_add_co_u32_e32 v42, vcc, s0, v14
	s_mov_b32 s0, 0x62000
	s_nop 0
	v_addc_co_u32_e32 v43, vcc, 0, v15, vcc
	v_add_co_u32_e32 v42, vcc, s24, v12
	v_add_f32_e32 v38, 1.0, v38
	s_nop 0
	v_addc_co_u32_e32 v43, vcc, 0, v13, vcc
	v_rcp_f32_e32 v38, v38
	v_lshlrev_b32_e32 v44, 16, v166
	v_mul_f32_e32 v42, 0xbfb8aa3b, v44
	v_exp_f32_e32 v42, v42
	v_lshlrev_b32_e32 v39, 16, v200
	v_add_f32_e32 v42, 1.0, v42
	v_rcp_f32_e32 v42, v42
	v_mul_f32_e32 v39, 0xbfb8aa3b, v39
	v_exp_f32_e32 v39, v39
	v_mul_f32_e32 v116, v42, v44
	v_add_co_u32_e32 v42, vcc, s0, v14
	s_mov_b32 s0, 0x61000
	s_nop 0
	v_addc_co_u32_e32 v43, vcc, 0, v15, vcc
	v_add_f32_e32 v39, 1.0, v39
	v_rcp_f32_e32 v39, v39
	v_lshlrev_b32_e32 v45, 16, v167
	v_add_co_u32_e32 v42, vcc, s0, v12
	s_mov_b32 s0, 0x66000
	s_nop 0
	v_addc_co_u32_e32 v43, vcc, 0, v13, vcc
	v_lshlrev_b32_e32 v42, 16, v201
	v_mul_f32_e32 v42, 0xbfb8aa3b, v42
	v_exp_f32_e32 v42, v42
	s_nop 0
	v_add_f32_e32 v42, 1.0, v42
	v_rcp_f32_e32 v44, v42
	v_mul_f32_e32 v42, 0xbfb8aa3b, v45
	v_exp_f32_e32 v42, v42
	s_nop 0
	v_add_f32_e32 v42, 1.0, v42
	v_rcp_f32_e32 v42, v42
	s_nop 0
	v_mul_f32_e32 v118, v42, v45
	v_add_co_u32_e32 v42, vcc, s0, v14
	s_mov_b32 s0, 0x6d000
	s_nop 0
	v_addc_co_u32_e32 v43, vcc, 0, v15, vcc
	v_lshlrev_b32_e32 v46, 16, v168
	v_add_co_u32_e32 v42, vcc, s25, v12
	s_nop 1
	v_addc_co_u32_e32 v43, vcc, 0, v13, vcc
	v_lshlrev_b32_e32 v42, 16, v202
	v_mul_f32_e32 v42, 0xbfb8aa3b, v42
	v_exp_f32_e32 v42, v42
	s_nop 0
	v_add_f32_e32 v42, 1.0, v42
	v_rcp_f32_e32 v45, v42
	v_mul_f32_e32 v42, 0xbfb8aa3b, v46
	v_exp_f32_e32 v42, v42
	s_nop 0
	v_add_f32_e32 v42, 1.0, v42
	v_rcp_f32_e32 v42, v42
	s_nop 0
	v_mul_f32_e32 v121, v42, v46
	v_add_co_u32_e32 v42, vcc, s13, v14
	s_nop 1
	v_addc_co_u32_e32 v43, vcc, 0, v15, vcc
	v_lshlrev_b32_e32 v46, 16, v169
	v_add_co_u32_e32 v42, vcc, s13, v12
	s_nop 1
	v_addc_co_u32_e32 v43, vcc, 0, v13, vcc
	v_mul_f32_e32 v43, 0xbfb8aa3b, v46
	v_exp_f32_e32 v43, v43
	v_lshlrev_b32_e32 v42, 16, v203
	v_add_f32_e32 v43, 1.0, v43
	v_rcp_f32_e32 v43, v43
	v_mul_f32_e32 v42, 0xbfb8aa3b, v42
	v_exp_f32_e32 v42, v42
	v_mul_f32_e32 v122, v43, v46
	v_add_co_u32_e32 v46, vcc, s0, v14
	s_mov_b32 s0, 0x71000
	s_nop 0
	v_addc_co_u32_e32 v47, vcc, 0, v15, vcc
	v_add_co_u32_e32 v46, vcc, s26, v12
	v_add_f32_e32 v42, 1.0, v42
	s_nop 0
	v_addc_co_u32_e32 v47, vcc, 0, v13, vcc
	v_rcp_f32_e32 v42, v42
	v_lshlrev_b32_e32 v78, 16, v170
	v_mul_f32_e32 v46, 0xbfb8aa3b, v78
	v_exp_f32_e32 v46, v46
	v_lshlrev_b32_e32 v43, 16, v204
	v_add_f32_e32 v46, 1.0, v46
	v_rcp_f32_e32 v46, v46
	v_mul_f32_e32 v43, 0xbfb8aa3b, v43
	v_exp_f32_e32 v43, v43
	v_mul_f32_e32 v123, v46, v78
	v_add_co_u32_e32 v46, vcc, s0, v14
	s_mov_b32 s0, 0x70000
	s_nop 0
	v_addc_co_u32_e32 v47, vcc, 0, v15, vcc
	v_add_f32_e32 v43, 1.0, v43
	v_rcp_f32_e32 v43, v43
	v_lshlrev_b32_e32 v78, 16, v171
	v_add_co_u32_e32 v46, vcc, s0, v12
	s_mov_b32 s0, 0x75000
	s_nop 0
	v_addc_co_u32_e32 v47, vcc, 0, v13, vcc
	v_add_co_u32_e32 v14, vcc, s0, v14
	s_nop 0
	v_addc_co_u32_e32 v15, vcc, 0, v15, vcc
	v_add_co_u32_e32 v12, vcc, s27, v12
	s_nop 0
	v_addc_co_u32_e32 v13, vcc, 0, v13, vcc
	v_mul_f32_e32 v47, 0xbfb8aa3b, v78
	v_exp_f32_e32 v47, v47
	s_mov_b32 s0, 0x3f317218
	v_add_f32_e32 v47, 1.0, v47
	v_rcp_f32_e32 v47, v47
	s_waitcnt vmcnt(2)
; #define GAS __attribute__((address_space(1)))
; #define LAS __attribute__((address_space(3)))
; DI unsigned pk2(float lo, float hi) { f32x2 v = {lo, hi}; bf16x2_t b = __builtin_convertvector(v, bf16x2_t); return __builtin_bit_cast(unsigned, b); }
; DI float bf2f(unsigned v) { return __uint_as_float(v << 16); }
; DI float fexp(float x) { return __builtin_amdgcn_exp2f(x * 1.4426950408889634f); }
; DI float flog(float x) { return __builtin_amdgcn_logf(x) * 0.6931471805599453f; }
; DI float frcp(float x) { return __builtin_amdgcn_rcpf(x); }
; DI float sigm(float x) { return frcp(1.f + fexp(-x)); }
; DI float silu(float x) { return x * sigm(x); }
; DI void hgrn_prep_job(const Frame& F, int job, int layer, LAS unsigned char* scr) {
;     ...
;         for (int t = 0; t < 32; ++t) {
;             const float qx = bf2f(qe[t]), fx = bf2f(fe[t]);
;             const float f = lb + (1.f - lb) * sigm(fx);
;             bsum += flog(f); bq[t] = bsum; kv[t] = 1.f - f; qv[t] = silu(qx);
;         }
;         ((GAS float*)he)[dk] = fexp(bsum);
; #pragma unroll
;         for (int t = 0; t < 32; ++t) {
;             const float e = fexp(bq[t]);
;             *(LAS bf16*)(QL + t * 272 + dk * 2) = (bf16)(pk2(qv[t] * e, 0.f) & 0xffffu);
;             *(LAS bf16*)(KL + t * 272 + dk * 2) = (bf16)(pk2(kv[t] * frcp(e), 0.f) & 0xffffu);
;             kv[t] = kv[t] * fexp(bsum - bq[t]);
;         }
	v_lshlrev_b32_e32 v46, 16, v205
	v_mul_f32_e32 v117, v47, v78
	v_mul_f32_e32 v46, 0xbfb8aa3b, v46
	v_exp_f32_e32 v46, v46
	s_waitcnt vmcnt(1)
	v_lshlrev_b32_e32 v14, 16, v172
	v_add_f32_e32 v46, 1.0, v46
	v_lshlrev_b32_e32 v12, 16, v206
	v_mul_f32_e32 v12, 0xbfb8aa3b, v12
	v_exp_f32_e32 v12, v12
	v_rcp_f32_e32 v46, v46
	v_add_f32_e32 v12, 1.0, v12
	v_rcp_f32_e32 v47, v12
	v_mul_f32_e32 v12, 0xbfb8aa3b, v14
	v_exp_f32_e32 v12, v12
	s_nop 0
	v_add_f32_e32 v12, 1.0, v12
	v_rcp_f32_e32 v12, v12
	s_nop 0
	v_mul_f32_e32 v120, v12, v14
	v_pk_fma_f32 v[14:15], v[6:7], v[16:17], v[4:5] op_sel_hi:[0,1,0]
	v_log_f32_e32 v16, v14
	v_lshl_add_u64 v[12:13], s[64:65], 0, v[10:11]
	v_pk_fma_f32 v[10:11], v[6:7], v[36:37], v[4:5] op_sel_hi:[0,1,0]
	v_log_f32_e32 v124, v10
	v_fma_f32 v128, v16, s0, 0
	v_log_f32_e32 v16, v15
	v_log_f32_e32 v125, v11
	v_pk_add_f32 v[36:37], v[10:11], 1.0 op_sel_hi:[1,0] neg_lo:[1,0] neg_hi:[1,0]
	v_pk_fma_f32 v[10:11], v[6:7], v[32:33], v[4:5] op_sel_hi:[0,1,0]
	v_fmamk_f32 v129, v16, 0x3f317218, v128
	v_mul_f32_e32 v16, 0x3fb8aa3b, v128
	v_exp_f32_e32 v130, v16
	v_add_co_u32_e32 v16, vcc, s14, v8
	v_log_f32_e32 v126, v10
	s_nop 0
	v_addc_co_u32_e32 v17, vcc, 0, v9, vcc
	global_load_ushort v78, v[16:17], off offset:3072
	v_add_co_u32_e32 v16, vcc, s15, v8
	v_log_f32_e32 v127, v11
	s_nop 0
	v_addc_co_u32_e32 v17, vcc, 0, v9, vcc
	global_load_ushort v79, v[16:17], off offset:1024
	v_add_co_u32_e32 v16, vcc, s20, v8
	v_pk_add_f32 v[32:33], v[10:11], 1.0 op_sel_hi:[1,0] neg_lo:[1,0] neg_hi:[1,0]
	s_nop 0
	v_addc_co_u32_e32 v17, vcc, 0, v9, vcc
	v_pk_fma_f32 v[10:11], v[6:7], v[24:25], v[4:5] op_sel_hi:[0,1,0]
	v_mul_f32_e32 v7, v7, v130
	global_load_ushort v80, v[16:17], off offset:3072
	v_add_co_u32_e32 v16, vcc, s21, v8
	v_cvt_pk_bf16_f32 v7, v7, s0
	s_nop 0
	v_addc_co_u32_e32 v17, vcc, 0, v9, vcc
	global_load_ushort v81, v[16:17], off offset:1024
	v_add_co_u32_e32 v16, vcc, s37, v8
	ds_write_b16 v119, v7
	v_rcp_f32_e32 v7, v130
	v_addc_co_u32_e32 v17, vcc, 0, v9, vcc
	global_load_ushort v82, v[16:17], off offset:3072
	v_add_co_u32_e32 v16, vcc, s5, v8
	v_pk_add_f32 v[14:15], v[14:15], 1.0 op_sel_hi:[1,0] neg_lo:[1,0] neg_hi:[1,0]
	s_nop 0
	v_addc_co_u32_e32 v17, vcc, 0, v9, vcc
	global_load_ushort v83, v[16:17], off offset:1024
	v_add_co_u32_e32 v16, vcc, s22, v8
	v_mul_f32_e32 v7, v14, v7
	s_nop 0
	v_addc_co_u32_e32 v17, vcc, 0, v9, vcc
	v_cvt_pk_bf16_f32 v7, v7, s0
	global_load_ushort v84, v[16:17], off offset:3072
	v_add_co_u32_e32 v16, vcc, s23, v8
	ds_write_b16 v119, v7 offset:8704
	v_mul_f32_e32 v7, 0x3fb8aa3b, v129
	v_addc_co_u32_e32 v17, vcc, 0, v9, vcc
	v_exp_f32_e32 v7, v7
	global_load_ushort v85, v[16:17], off offset:1024
	v_add_co_u32_e32 v16, vcc, s17, v8
	v_mul_f32_e32 v5, v5, v7
	s_nop 0
	v_addc_co_u32_e32 v17, vcc, 0, v9, vcc
	global_load_ushort v86, v[16:17], off offset:3072
	v_add_co_u32_e32 v16, vcc, s18, v8
	v_cvt_pk_bf16_f32 v5, v5, s0
	s_nop 0
	v_addc_co_u32_e32 v17, vcc, 0, v9, vcc
	global_load_ushort v87, v[16:17], off offset:1024
	v_add_co_u32_e32 v16, vcc, s24, v8
	ds_write_b16 v119, v5 offset:272
	s_nop 0
	v_addc_co_u32_e32 v17, vcc, 0, v9, vcc
	v_rcp_f32_e32 v5, v7
	v_log_f32_e32 v24, v10
	global_load_ushort v88, v[16:17], off offset:3072
	v_add_co_u32_e32 v16, vcc, s25, v8
	v_mul_f32_e32 v5, v15, v5
	s_nop 0
	v_addc_co_u32_e32 v17, vcc, 0, v9, vcc
	global_load_ushort v89, v[16:17], off offset:1024
	v_add_co_u32_e32 v16, vcc, s96, v8
	v_cvt_pk_bf16_f32 v5, v5, s0
	s_nop 0
	v_addc_co_u32_e32 v17, vcc, 0, v9, vcc
	global_load_ushort v90, v[16:17], off offset:3072
	v_add_co_u32_e32 v16, vcc, s19, v8
	v_fmamk_f32 v7, v24, 0x3f317218, v129
	s_nop 0
	v_addc_co_u32_e32 v17, vcc, 0, v9, vcc
	ds_write_b16 v119, v5 offset:8976
	v_mul_f32_e32 v5, 0x3fb8aa3b, v7
	global_load_ushort v92, v[16:17], off offset:1024
	v_add_co_u32_e32 v16, vcc, s26, v8
	v_exp_f32_e32 v5, v5
	s_nop 0
	v_addc_co_u32_e32 v17, vcc, 0, v9, vcc
	v_add_co_u32_e32 v8, vcc, s27, v8
	global_load_ushort v93, v[16:17], off offset:3072
	s_nop 0
	v_addc_co_u32_e32 v9, vcc, 0, v9, vcc
	global_load_ushort v94, v[8:9], off offset:1024
	v_mul_f32_e32 v8, v74, v5
	v_rcp_f32_e32 v5, v5
	v_log_f32_e32 v25, v11
	v_pk_add_f32 v[10:11], v[10:11], 1.0 op_sel_hi:[1,0] neg_lo:[1,0] neg_hi:[1,0]
	v_cvt_pk_bf16_f32 v8, v8, s0
	v_mul_f32_e32 v5, v10, v5
	v_fmamk_f32 v130, v25, 0x3f317218, v7
	v_cvt_pk_bf16_f32 v5, v5, s0
	ds_write_b16 v119, v5 offset:9248
	v_mul_f32_e32 v5, 0x3fb8aa3b, v130
	v_exp_f32_e32 v5, v5
	ds_write_b16 v119, v8 offset:544
	s_and_b64 vcc, exec, s[82:83]
	s_mov_b64 s[82:83], 0
	v_mul_f32_e32 v8, v76, v5
	v_rcp_f32_e32 v5, v5
	v_cvt_pk_bf16_f32 v8, v8, s0
	ds_write_b16 v119, v8 offset:816
	v_mul_f32_e32 v5, v11, v5
	v_cvt_pk_bf16_f32 v5, v5, s0
	v_pk_fma_f32 v[8:9], v[6:7], v[40:41], v[4:5] op_sel_hi:[0,1,0]
	v_log_f32_e32 v74, v8
	v_log_f32_e32 v76, v9
	v_pk_add_f32 v[40:41], v[8:9], 1.0 op_sel_hi:[1,0] neg_lo:[1,0] neg_hi:[1,0]
	v_pk_fma_f32 v[8:9], v[6:7], v[34:35], v[4:5] op_sel_hi:[0,1,0]
	v_log_f32_e32 v131, v8
	v_log_f32_e32 v132, v9
	v_pk_add_f32 v[24:25], v[8:9], 1.0 op_sel_hi:[1,0] neg_lo:[1,0] neg_hi:[1,0]
	v_pk_fma_f32 v[8:9], v[6:7], v[22:23], v[4:5] op_sel_hi:[0,1,0]
	ds_write_b16 v119, v5 offset:9520
	v_log_f32_e32 v5, v8
	v_log_f32_e32 v22, v9
	v_pk_add_f32 v[16:17], v[8:9], 1.0 op_sel_hi:[1,0] neg_lo:[1,0] neg_hi:[1,0]
	v_pk_fma_f32 v[8:9], v[6:7], v[18:19], v[4:5] op_sel_hi:[0,1,0]
	v_log_f32_e32 v18, v8
	v_log_f32_e32 v19, v9
	v_pk_add_f32 v[8:9], v[8:9], 1.0 op_sel_hi:[1,0] neg_lo:[1,0] neg_hi:[1,0]
	v_fmamk_f32 v133, v18, 0x3f317218, v130
	v_mul_f32_e32 v18, 0x3fb8aa3b, v133
	v_exp_f32_e32 v18, v18
; #define LAS __attribute__((address_space(3)))
; DI unsigned pk2(float lo, float hi) { f32x2 v = {lo, hi}; bf16x2_t b = __builtin_convertvector(v, bf16x2_t); return __builtin_bit_cast(unsigned, b); }
; DI float fexp(float x) { return __builtin_amdgcn_exp2f(x * 1.4426950408889634f); }
; DI float frcp(float x) { return __builtin_amdgcn_rcpf(x); }
; DI void hgrn_prep_job(const Frame& F, int job, int layer, LAS unsigned char* scr) {
;     ...
; #pragma unroll
;         for (int t = 0; t < 32; ++t) {
;             const float e = fexp(bq[t]);
;             *(LAS bf16*)(QL + t * 272 + dk * 2) = (bf16)(pk2(qv[t] * e, 0.f) & 0xffffu);
;             *(LAS bf16*)(KL + t * 272 + dk * 2) = (bf16)(pk2(kv[t] * frcp(e), 0.f) & 0xffffu);
;             kv[t] = kv[t] * fexp(bsum - bq[t]);
;         }
	v_fmamk_f32 v134, v19, 0x3f317218, v133
	v_mul_f32_e32 v19, v75, v18
	v_rcp_f32_e32 v18, v18
	v_cvt_pk_bf16_f32 v19, v19, s0
	ds_write_b16 v119, v19 offset:1088
	v_fmamk_f32 v75, v5, 0x3f317218, v134
	v_mul_f32_e32 v18, v8, v18
	v_cvt_pk_bf16_f32 v18, v18, s0
	ds_write_b16 v119, v18 offset:9792
	v_mul_f32_e32 v18, 0x3fb8aa3b, v134
	v_exp_f32_e32 v18, v18
	v_mul_f32_e32 v5, 0x3fb8aa3b, v75
	v_exp_f32_e32 v5, v5
	v_mul_f32_e32 v19, v77, v18
	v_rcp_f32_e32 v18, v18
	v_fmamk_f32 v77, v22, 0x3f317218, v75
	v_cvt_pk_bf16_f32 v19, v19, s0
	ds_write_b16 v119, v19 offset:1360
	v_mul_f32_e32 v18, v9, v18
	v_cvt_pk_bf16_f32 v18, v18, s0
	ds_write_b16 v119, v18 offset:10064
	v_mul_f32_e32 v18, v91, v5
	v_rcp_f32_e32 v5, v5
	v_cvt_pk_bf16_f32 v18, v18, s0
	ds_write_b16 v119, v18 offset:1632
	v_mul_f32_e32 v5, v16, v5
	v_cvt_pk_bf16_f32 v5, v5, s0
	ds_write_b16 v119, v5 offset:10336
	v_mul_f32_e32 v5, 0x3fb8aa3b, v77
	v_exp_f32_e32 v5, v5
	s_nop 0
	v_mul_f32_e32 v18, v99, v5
	v_rcp_f32_e32 v5, v5
	v_cvt_pk_bf16_f32 v18, v18, s0
	ds_write_b16 v119, v18 offset:1904
	v_mul_f32_e32 v5, v17, v5
	v_cvt_pk_bf16_f32 v5, v5, s0
	v_pk_fma_f32 v[18:19], v[6:7], v[44:45], v[4:5] op_sel_hi:[0,1,0]
	v_log_f32_e32 v91, v18
	v_log_f32_e32 v99, v19
	v_pk_add_f32 v[34:35], v[18:19], 1.0 op_sel_hi:[1,0] neg_lo:[1,0] neg_hi:[1,0]
	v_pk_fma_f32 v[18:19], v[6:7], v[38:39], v[4:5] op_sel_hi:[0,1,0]
	v_log_f32_e32 v135, v18
	v_log_f32_e32 v136, v19
	v_pk_add_f32 v[38:39], v[18:19], 1.0 op_sel_hi:[1,0] neg_lo:[1,0] neg_hi:[1,0]
	v_pk_fma_f32 v[18:19], v[6:7], v[28:29], v[4:5] op_sel_hi:[0,1,0]
	ds_write_b16 v119, v5 offset:10608
	v_log_f32_e32 v5, v18
	v_log_f32_e32 v22, v19
	v_pk_add_f32 v[18:19], v[18:19], 1.0 op_sel_hi:[1,0] neg_lo:[1,0] neg_hi:[1,0]
	v_pk_fma_f32 v[20:21], v[6:7], v[20:21], v[4:5] op_sel_hi:[0,1,0]
	v_log_f32_e32 v23, v20
	v_log_f32_e32 v28, v21
	v_pk_add_f32 v[20:21], v[20:21], 1.0 op_sel_hi:[1,0] neg_lo:[1,0] neg_hi:[1,0]
	v_fmamk_f32 v29, v23, 0x3f317218, v77
	v_mul_f32_e32 v23, 0x3fb8aa3b, v29
	v_exp_f32_e32 v23, v23
	v_fmamk_f32 v28, v28, 0x3f317218, v29
	v_mul_f32_e32 v44, v95, v23
	v_rcp_f32_e32 v23, v23
	v_fmamk_f32 v95, v5, 0x3f317218, v28
	v_mul_f32_e32 v5, 0x3fb8aa3b, v95
	v_exp_f32_e32 v5, v5
	v_mul_f32_e32 v23, v20, v23
	v_cvt_pk_bf16_f32 v23, v23, s0
	ds_write_b16 v119, v23 offset:10880
	v_mul_f32_e32 v23, 0x3fb8aa3b, v28
	v_exp_f32_e32 v23, v23
	v_cvt_pk_bf16_f32 v44, v44, s0
	ds_write_b16 v119, v44 offset:2176
	v_mul_f32_e32 v44, v98, v23
	v_fmamk_f32 v98, v22, 0x3f317218, v95
	v_mul_f32_e32 v22, v101, v5
	v_rcp_f32_e32 v5, v5
	v_cvt_pk_bf16_f32 v22, v22, s0
	v_rcp_f32_e32 v23, v23
	ds_write_b16 v119, v22 offset:2720
	v_mul_f32_e32 v5, v18, v5
	v_cvt_pk_bf16_f32 v5, v5, s0
	ds_write_b16 v119, v5 offset:11424
	v_mul_f32_e32 v5, 0x3fb8aa3b, v98
	v_exp_f32_e32 v5, v5
	v_mul_f32_e32 v23, v21, v23
	v_cvt_pk_bf16_f32 v23, v23, s0
	v_cvt_pk_bf16_f32 v44, v44, s0
	v_mul_f32_e32 v22, v103, v5
	v_rcp_f32_e32 v5, v5
	v_cvt_pk_bf16_f32 v22, v22, s0
	ds_write_b16 v119, v23 offset:11152
	ds_write_b16 v119, v22 offset:2992
	v_mul_f32_e32 v5, v19, v5
	v_cvt_pk_bf16_f32 v5, v5, s0
	v_pk_fma_f32 v[22:23], v[6:7], v[46:47], v[4:5] op_sel_hi:[0,1,0]
	ds_write_b16 v119, v44 offset:2448
	v_log_f32_e32 v46, v22
	v_log_f32_e32 v47, v23
	v_pk_add_f32 v[44:45], v[22:23], 1.0 op_sel_hi:[1,0] neg_lo:[1,0] neg_hi:[1,0]
	v_pk_fma_f32 v[22:23], v[6:7], v[42:43], v[4:5] op_sel_hi:[0,1,0]
	ds_write_b16 v119, v5 offset:11696
	v_log_f32_e32 v101, v22
	v_log_f32_e32 v103, v23
	v_pk_add_f32 v[42:43], v[22:23], 1.0 op_sel_hi:[1,0] neg_lo:[1,0] neg_hi:[1,0]
	v_pk_fma_f32 v[22:23], v[6:7], v[30:31], v[4:5] op_sel_hi:[0,1,0]
	v_pk_fma_f32 v[4:5], v[6:7], v[26:27], v[4:5] op_sel_hi:[0,1,0]
	v_log_f32_e32 v6, v4
	v_pk_add_f32 v[26:27], v[4:5], 1.0 op_sel_hi:[1,0] neg_lo:[1,0] neg_hi:[1,0]
	v_log_f32_e32 v137, v5
	v_log_f32_e32 v30, v22
	v_fmamk_f32 v138, v6, 0x3f317218, v98
	v_mul_f32_e32 v4, 0x3fb8aa3b, v138
	v_exp_f32_e32 v4, v4
	v_fmamk_f32 v137, v137, 0x3f317218, v138
	v_fmamk_f32 v30, v30, 0x3f317218, v137
	v_log_f32_e32 v31, v23
	v_mul_f32_e32 v5, v102, v4
	v_rcp_f32_e32 v4, v4
	v_cvt_pk_bf16_f32 v5, v5, s0
	ds_write_b16 v119, v5 offset:3264
	v_pk_add_f32 v[22:23], v[22:23], 1.0 op_sel_hi:[1,0] neg_lo:[1,0] neg_hi:[1,0]
	v_mul_f32_e32 v4, v26, v4
	v_cvt_pk_bf16_f32 v4, v4, s0
	ds_write_b16 v119, v4 offset:11968
	v_mul_f32_e32 v4, 0x3fb8aa3b, v137
	v_exp_f32_e32 v4, v4
	v_fmamk_f32 v31, v31, 0x3f317218, v30
	v_fmamk_f32 v102, v126, 0x3f317218, v31
	v_mul_f32_e32 v5, v104, v4
	v_rcp_f32_e32 v4, v4
	v_cvt_pk_bf16_f32 v5, v5, s0
	ds_write_b16 v119, v5 offset:3536
	v_fmamk_f32 v104, v127, 0x3f317218, v102
	v_mul_f32_e32 v4, v27, v4
	v_cvt_pk_bf16_f32 v4, v4, s0
	ds_write_b16 v119, v4 offset:12240
	v_mul_f32_e32 v4, 0x3fb8aa3b, v30
	v_exp_f32_e32 v4, v4
	s_nop 0
	v_mul_f32_e32 v5, v105, v4
	v_rcp_f32_e32 v4, v4
	v_cvt_pk_bf16_f32 v5, v5, s0
	ds_write_b16 v119, v5 offset:3808
	v_fmamk_f32 v105, v124, 0x3f317218, v104
	v_mul_f32_e32 v4, v22, v4
	v_cvt_pk_bf16_f32 v4, v4, s0
	ds_write_b16 v119, v4 offset:12512
	v_mul_f32_e32 v4, 0x3fb8aa3b, v31
	v_exp_f32_e32 v4, v4
	s_nop 0
	v_mul_f32_e32 v5, v106, v4
	v_rcp_f32_e32 v4, v4
	v_cvt_pk_bf16_f32 v5, v5, s0
	ds_write_b16 v119, v5 offset:4080
	v_fmamk_f32 v106, v125, 0x3f317218, v105
	v_mul_f32_e32 v4, v23, v4
	v_cvt_pk_bf16_f32 v4, v4, s0
	ds_write_b16 v119, v4 offset:12784
	v_mul_f32_e32 v4, 0x3fb8aa3b, v102
	v_exp_f32_e32 v4, v4
	s_nop 0
	v_mul_f32_e32 v5, v107, v4
	v_rcp_f32_e32 v4, v4
	v_cvt_pk_bf16_f32 v5, v5, s0
	ds_write_b16 v119, v5 offset:4352
	v_fmamk_f32 v107, v131, 0x3f317218, v106
	v_mul_f32_e32 v4, v32, v4
; #define GAS __attribute__((address_space(1)))
; #define LAS __attribute__((address_space(3)))
; DI unsigned pk2(float lo, float hi) { f32x2 v = {lo, hi}; bf16x2_t b = __builtin_convertvector(v, bf16x2_t); return __builtin_bit_cast(unsigned, b); }
; DI float fexp(float x) { return __builtin_amdgcn_exp2f(x * 1.4426950408889634f); }
; DI float frcp(float x) { return __builtin_amdgcn_rcpf(x); }
; DI void hgrn_prep_job(const Frame& F, int job, int layer, LAS unsigned char* scr) {
;     ...
;         ((GAS float*)he)[dk] = fexp(bsum);
; #pragma unroll
;         for (int t = 0; t < 32; ++t) {
;             const float e = fexp(bq[t]);
;             *(LAS bf16*)(QL + t * 272 + dk * 2) = (bf16)(pk2(qv[t] * e, 0.f) & 0xffffu);
;             *(LAS bf16*)(KL + t * 272 + dk * 2) = (bf16)(pk2(kv[t] * frcp(e), 0.f) & 0xffffu);
;             kv[t] = kv[t] * fexp(bsum - bq[t]);
;         }
	v_cvt_pk_bf16_f32 v4, v4, s0
	ds_write_b16 v119, v4 offset:13056
	v_mul_f32_e32 v4, 0x3fb8aa3b, v104
	v_exp_f32_e32 v4, v4
	s_nop 0
	v_mul_f32_e32 v5, v108, v4
	v_rcp_f32_e32 v4, v4
	v_cvt_pk_bf16_f32 v5, v5, s0
	ds_write_b16 v119, v5 offset:4624
	v_fmamk_f32 v108, v132, 0x3f317218, v107
	v_mul_f32_e32 v4, v33, v4
	v_cvt_pk_bf16_f32 v4, v4, s0
	ds_write_b16 v119, v4 offset:13328
	v_mul_f32_e32 v4, 0x3fb8aa3b, v105
	v_exp_f32_e32 v4, v4
	v_fmamk_f32 v74, v74, 0x3f317218, v108
	v_fmamk_f32 v76, v76, 0x3f317218, v74
	v_mul_f32_e32 v5, v109, v4
	v_rcp_f32_e32 v4, v4
	v_cvt_pk_bf16_f32 v5, v5, s0
	ds_write_b16 v119, v5 offset:4896
	v_fmamk_f32 v109, v135, 0x3f317218, v76
	v_mul_f32_e32 v4, v36, v4
	v_cvt_pk_bf16_f32 v4, v4, s0
	ds_write_b16 v119, v4 offset:13600
	v_mul_f32_e32 v4, 0x3fb8aa3b, v106
	v_exp_f32_e32 v4, v4
	s_nop 0
	v_mul_f32_e32 v5, v110, v4
	v_rcp_f32_e32 v4, v4
	v_cvt_pk_bf16_f32 v5, v5, s0
	ds_write_b16 v119, v5 offset:5168
	v_fmamk_f32 v110, v136, 0x3f317218, v109
	v_mul_f32_e32 v4, v37, v4
	v_cvt_pk_bf16_f32 v4, v4, s0
	ds_write_b16 v119, v4 offset:13872
	v_mul_f32_e32 v4, 0x3fb8aa3b, v107
	v_exp_f32_e32 v4, v4
	v_fmamk_f32 v91, v91, 0x3f317218, v110
	v_fmamk_f32 v99, v99, 0x3f317218, v91
	v_fmamk_f32 v101, v101, 0x3f317218, v99
	v_mul_f32_e32 v5, v111, v4
	v_rcp_f32_e32 v4, v4
	v_cvt_pk_bf16_f32 v5, v5, s0
	ds_write_b16 v119, v5 offset:5440
	v_fmamk_f32 v103, v103, 0x3f317218, v101
	v_mul_f32_e32 v4, v24, v4
	v_cvt_pk_bf16_f32 v4, v4, s0
	ds_write_b16 v119, v4 offset:14144
	v_mul_f32_e32 v4, 0x3fb8aa3b, v108
	v_exp_f32_e32 v4, v4
	v_fmamk_f32 v46, v46, 0x3f317218, v103
	v_fmamk_f32 v47, v47, 0x3f317218, v46
	v_sub_f32_e32 v6, v47, v7
	v_mul_f32_e32 v5, v112, v4
	v_rcp_f32_e32 v4, v4
	v_cvt_pk_bf16_f32 v5, v5, s0
	ds_write_b16 v119, v5 offset:5712
	v_sub_f32_e32 v7, v47, v130
	v_mul_f32_e32 v4, v25, v4
	v_cvt_pk_bf16_f32 v4, v4, s0
	ds_write_b16 v119, v4 offset:14416
	v_mul_f32_e32 v4, 0x3fb8aa3b, v74
	v_exp_f32_e32 v4, v4
	v_mul_f32_e32 v6, 0x3fb8aa3b, v6
	v_mul_f32_e32 v7, 0x3fb8aa3b, v7
	v_exp_f32_e32 v6, v6
	v_mul_f32_e32 v5, v113, v4
	v_rcp_f32_e32 v4, v4
	v_cvt_pk_bf16_f32 v5, v5, s0
	ds_write_b16 v119, v5 offset:5984
	v_exp_f32_e32 v7, v7
	v_mul_f32_e32 v4, v40, v4
	v_cvt_pk_bf16_f32 v4, v4, s0
	ds_write_b16 v119, v4 offset:14688
	v_mul_f32_e32 v4, 0x3fb8aa3b, v76
	v_exp_f32_e32 v4, v4
	v_pk_mul_f32 v[6:7], v[10:11], v[6:7]
	v_sub_f32_e32 v10, v47, v133
	v_sub_f32_e32 v11, v47, v134
	v_mul_f32_e32 v5, v114, v4
	v_rcp_f32_e32 v4, v4
	v_cvt_pk_bf16_f32 v5, v5, s0
	ds_write_b16 v119, v5 offset:6256
	v_mul_f32_e32 v10, 0x3fb8aa3b, v10
	v_mul_f32_e32 v4, v41, v4
	v_cvt_pk_bf16_f32 v4, v4, s0
	ds_write_b16 v119, v4 offset:14960
	v_mul_f32_e32 v4, 0x3fb8aa3b, v109
	v_exp_f32_e32 v4, v4
	v_mul_f32_e32 v11, 0x3fb8aa3b, v11
	v_exp_f32_e32 v10, v10
	v_exp_f32_e32 v11, v11
	v_mul_f32_e32 v5, v115, v4
	v_rcp_f32_e32 v4, v4
	v_cvt_pk_bf16_f32 v5, v5, s0
	ds_write_b16 v119, v5 offset:6528
	v_pk_mul_f32 v[8:9], v[8:9], v[10:11]
	v_mul_f32_e32 v4, v38, v4
	v_cvt_pk_bf16_f32 v4, v4, s0
	ds_write_b16 v119, v4 offset:15232
	v_mul_f32_e32 v4, 0x3fb8aa3b, v110
	v_exp_f32_e32 v4, v4
	v_sub_f32_e32 v10, v47, v75
	v_sub_f32_e32 v11, v47, v77
	v_mul_f32_e32 v10, 0x3fb8aa3b, v10
	v_mul_f32_e32 v5, v116, v4
	v_rcp_f32_e32 v4, v4
	v_cvt_pk_bf16_f32 v5, v5, s0
	ds_write_b16 v119, v5 offset:6800
	v_mul_f32_e32 v11, 0x3fb8aa3b, v11
	v_mul_f32_e32 v4, v39, v4
	v_cvt_pk_bf16_f32 v4, v4, s0
	ds_write_b16 v119, v4 offset:15504
	v_mul_f32_e32 v4, 0x3fb8aa3b, v91
	v_exp_f32_e32 v4, v4
	v_exp_f32_e32 v10, v10
	v_exp_f32_e32 v11, v11
	v_mul_f32_e32 v5, v118, v4
	v_rcp_f32_e32 v4, v4
	v_cvt_pk_bf16_f32 v5, v5, s0
	ds_write_b16 v119, v5 offset:7072
	v_pk_mul_f32 v[10:11], v[16:17], v[10:11]
	v_mul_f32_e32 v4, v34, v4
	v_cvt_pk_bf16_f32 v4, v4, s0
	ds_write_b16 v119, v4 offset:15776
	v_mul_f32_e32 v4, 0x3fb8aa3b, v99
	v_exp_f32_e32 v4, v4
	v_sub_f32_e32 v16, v47, v138
	v_sub_f32_e32 v17, v47, v137
	v_mul_f32_e32 v16, 0x3fb8aa3b, v16
	v_mul_f32_e32 v5, v121, v4
	v_rcp_f32_e32 v4, v4
	v_cvt_pk_bf16_f32 v5, v5, s0
	ds_write_b16 v119, v5 offset:7344
	v_mul_f32_e32 v17, 0x3fb8aa3b, v17
	v_mul_f32_e32 v4, v35, v4
	v_cvt_pk_bf16_f32 v4, v4, s0
	ds_write_b16 v119, v4 offset:16048
	v_mul_f32_e32 v4, 0x3fb8aa3b, v101
	v_exp_f32_e32 v4, v4
	v_exp_f32_e32 v16, v16
	v_exp_f32_e32 v17, v17
	v_mul_f32_e32 v5, v122, v4
	v_rcp_f32_e32 v4, v4
	v_cvt_pk_bf16_f32 v5, v5, s0
	ds_write_b16 v119, v5 offset:7616
	v_pk_mul_f32 v[16:17], v[26:27], v[16:17]
	v_mul_f32_e32 v4, v42, v4
	v_cvt_pk_bf16_f32 v4, v4, s0
	ds_write_b16 v119, v4 offset:16320
	v_mul_f32_e32 v4, 0x3fb8aa3b, v103
	v_exp_f32_e32 v4, v4
	v_sub_f32_e32 v26, v47, v107
	v_sub_f32_e32 v27, v47, v108
	v_mul_f32_e32 v26, 0x3fb8aa3b, v26
	v_mul_f32_e32 v5, v123, v4
	v_rcp_f32_e32 v4, v4
	v_cvt_pk_bf16_f32 v5, v5, s0
	ds_write_b16 v119, v5 offset:7888
	v_sub_f32_e32 v5, v47, v129
	v_mul_f32_e32 v4, v43, v4
	v_cvt_pk_bf16_f32 v4, v4, s0
	ds_write_b16 v119, v4 offset:16592
	v_mul_f32_e32 v4, 0x3fb8aa3b, v47
	v_exp_f32_e32 v111, v4
	v_sub_f32_e32 v4, v47, v128
	v_mul_f32_e32 v4, 0x3fb8aa3b, v4
	v_mul_f32_e32 v5, 0x3fb8aa3b, v5
	v_exp_f32_e32 v4, v4
	v_exp_f32_e32 v5, v5
	global_store_dword v[12:13], v111, off
	v_sub_f32_e32 v12, v47, v29
	v_sub_f32_e32 v13, v47, v28
	v_pk_mul_f32 v[4:5], v[14:15], v[4:5]
	v_sub_f32_e32 v14, v47, v95
	v_sub_f32_e32 v15, v47, v98
	v_mul_f32_e32 v14, 0x3fb8aa3b, v14
	v_mul_f32_e32 v15, 0x3fb8aa3b, v15
	v_exp_f32_e32 v14, v14
	v_exp_f32_e32 v15, v15
	v_mul_f32_e32 v12, 0x3fb8aa3b, v12
	v_mul_f32_e32 v13, 0x3fb8aa3b, v13
	v_exp_f32_e32 v12, v12
	v_pk_mul_f32 v[14:15], v[18:19], v[14:15]
; #define GAS __attribute__((address_space(1)))
; DI unsigned pk2(float lo, float hi) { f32x2 v = {lo, hi}; bf16x2_t b = __builtin_convertvector(v, bf16x2_t); return __builtin_bit_cast(unsigned, b); }
; DI float fexp(float x) { return __builtin_amdgcn_exp2f(x * 1.4426950408889634f); }
; DI void hgrn_prep_job(const Frame& F, int job, int layer, LAS unsigned char* scr) {
;     ...
;             kv[t] = kv[t] * fexp(bsum - bq[t]);
;         }
; #pragma unroll
;         for (int g = 0; g < 4; ++g) {
;             v4u w; w.x = pk2(kv[permk(g, 0)], kv[permk(g, 1)]); w.y = pk2(kv[permk(g, 2)], kv[permk(g, 3)]); w.z = pk2(kv[permk(g, 4)], kv[permk(g, 5)]); w.w = pk2(kv[permk(g, 6)], kv[permk(g, 7)]);
;             *(GAS v4u*)(hk + (((dk >> 4) * 64) + (dk & 15) + 16 * g) * 16) = w;
;         }
; #pragma unroll
;         for (int g = 0; g < 4; ++g) {
;             v4u w; w.x = ve[permk(g, 0)] | ((unsigned)ve[permk(g, 1)] << 16); w.y = ve[permk(g, 2)] | ((unsigned)ve[permk(g, 3)] << 16);
;             w.z = ve[permk(g, 4)] | ((unsigned)ve[permk(g, 5)] << 16); w.w = ve[permk(g, 6)] | ((unsigned)ve[permk(g, 7)] << 16);
;             *(GAS v4u*)(hv + (((dk >> 4) * 64) + (dk & 15) + 16 * g) * 16) = w;
;         }
	v_sub_f32_e32 v18, v47, v30
	v_sub_f32_e32 v19, v47, v31
	v_sub_f32_e32 v30, v47, v91
	v_sub_f32_e32 v31, v47, v99
	v_mul_f32_e32 v30, 0x3fb8aa3b, v30
	v_mul_f32_e32 v31, 0x3fb8aa3b, v31
	v_exp_f32_e32 v30, v30
	v_exp_f32_e32 v31, v31
	v_exp_f32_e32 v13, v13
	v_mul_f32_e32 v18, 0x3fb8aa3b, v18
	v_mul_f32_e32 v19, 0x3fb8aa3b, v19
	v_pk_mul_f32 v[30:31], v[34:35], v[30:31]
	v_mul_f32_e32 v34, 0x3fb8aa3b, v46
	v_exp_f32_e32 v34, v34
	v_exp_f32_e32 v18, v18
	v_exp_f32_e32 v19, v19
	v_mul_f32_e32 v27, 0x3fb8aa3b, v27
	v_mul_f32_e32 v35, v117, v34
	v_cvt_pk_bf16_f32 v35, v35, s0
	ds_write_b16 v119, v35 offset:8160
	v_mul_f32_e32 v35, v120, v111
	v_cvt_pk_bf16_f32 v35, v35, s0
	v_pk_mul_f32 v[12:13], v[20:21], v[12:13]
	v_sub_f32_e32 v20, v47, v102
	v_sub_f32_e32 v21, v47, v104
	v_exp_f32_e32 v26, v26
	v_exp_f32_e32 v27, v27
	v_rcp_f32_e32 v34, v34
	ds_write_b16 v119, v35 offset:8432
	v_rcp_f32_e32 v35, v111
	v_mul_f32_e32 v20, 0x3fb8aa3b, v20
	v_mul_f32_e32 v21, 0x3fb8aa3b, v21
	v_pk_mul_f32 v[18:19], v[22:23], v[18:19]
	v_exp_f32_e32 v20, v20
	v_exp_f32_e32 v21, v21
	v_sub_f32_e32 v22, v47, v105
	v_sub_f32_e32 v23, v47, v106
	v_mul_f32_e32 v22, 0x3fb8aa3b, v22
	v_mul_f32_e32 v23, 0x3fb8aa3b, v23
	v_exp_f32_e32 v22, v22
	v_exp_f32_e32 v23, v23
	v_pk_mul_f32 v[24:25], v[24:25], v[26:27]
	v_sub_f32_e32 v26, v47, v74
	v_sub_f32_e32 v27, v47, v76
	v_mul_f32_e32 v34, v44, v34
	v_mul_f32_e32 v35, v45, v35
	v_mul_f32_e32 v26, 0x3fb8aa3b, v26
	v_mul_f32_e32 v27, 0x3fb8aa3b, v27
	v_sub_f32_e32 v28, v47, v109
	v_sub_f32_e32 v29, v47, v110
	v_cvt_pk_bf16_f32 v34, v34, s0
	v_cvt_pk_bf16_f32 v35, v35, s0
	v_pk_mul_f32 v[20:21], v[32:33], v[20:21]
	v_exp_f32_e32 v26, v26
	v_exp_f32_e32 v27, v27
	v_mul_f32_e32 v28, 0x3fb8aa3b, v28
	v_mul_f32_e32 v29, 0x3fb8aa3b, v29
	v_sub_f32_e32 v32, v47, v101
	v_sub_f32_e32 v33, v47, v103
	ds_write_b16 v119, v34 offset:16864
	v_sub_f32_e32 v34, v47, v46
	ds_write_b16 v119, v35 offset:17136
	v_sub_f32_e32 v35, v47, v47
	v_exp_f32_e32 v28, v28
	v_exp_f32_e32 v29, v29
	v_mul_f32_e32 v32, 0x3fb8aa3b, v32
	v_mul_f32_e32 v33, 0x3fb8aa3b, v33
	v_mul_f32_e32 v34, 0x3fb8aa3b, v34
	v_mul_f32_e32 v35, 0x3fb8aa3b, v35
	v_pk_mul_f32 v[22:23], v[36:37], v[22:23]
	v_exp_f32_e32 v32, v32
	v_exp_f32_e32 v33, v33
	v_exp_f32_e32 v34, v34
	v_exp_f32_e32 v35, v35
	v_lshlrev_b32_e32 v36, 2, v96
	s_movk_i32 s0, 0x1c0
	v_and_or_b32 v36, v36, s0, v49
	v_pk_mul_f32 v[26:27], v[40:41], v[26:27]
	v_lshlrev_b32_e32 v36, 4, v36
	v_cvt_pk_bf16_f32 v4, v4, v5
	v_cvt_pk_bf16_f32 v5, v6, v7
	v_cvt_pk_bf16_f32 v6, v20, v21
	v_cvt_pk_bf16_f32 v7, v22, v23
	v_pk_mul_f32 v[28:29], v[38:39], v[28:29]
	global_store_dwordx4 v36, v[4:7], s[60:61]
	v_pk_mul_f32 v[32:33], v[42:43], v[32:33]
	v_pk_mul_f32 v[34:35], v[44:45], v[34:35]
	v_cvt_pk_bf16_f32 v4, v8, v9
	v_cvt_pk_bf16_f32 v5, v10, v11
	v_cvt_pk_bf16_f32 v6, v24, v25
	v_cvt_pk_bf16_f32 v7, v26, v27
	global_store_dwordx4 v36, v[4:7], s[60:61] offset:256
	s_mov_b32 s0, 64
	s_nop 0
	v_cvt_pk_bf16_f32 v4, v12, v13
	v_cvt_pk_bf16_f32 v5, v14, v15
	v_cvt_pk_bf16_f32 v6, v28, v29
	v_cvt_pk_bf16_f32 v7, v30, v31
	global_store_dwordx4 v36, v[4:7], s[60:61] offset:512
	s_nop 1
	v_cvt_pk_bf16_f32 v4, v16, v17
	v_cvt_pk_bf16_f32 v5, v18, v19
	v_cvt_pk_bf16_f32 v6, v32, v33
	v_cvt_pk_bf16_f32 v7, v34, v35
	global_store_dwordx4 v36, v[4:7], s[60:61] offset:768
	s_waitcnt vmcnt(20)
	s_nop 0
	v_lshl_or_b32 v4, v78, 16, v58
	s_waitcnt vmcnt(19)
	v_lshl_or_b32 v5, v79, 16, v59
	s_waitcnt vmcnt(18)
	v_lshl_or_b32 v6, v80, 16, v66
	s_waitcnt vmcnt(17)
	v_lshl_or_b32 v7, v81, 16, v67
	global_store_dwordx4 v36, v[4:7], s[62:63]
	s_waitcnt vmcnt(17)
	s_nop 0
	v_lshl_or_b32 v4, v82, 16, v60
	s_waitcnt vmcnt(16)
	v_lshl_or_b32 v5, v83, 16, v61
	s_waitcnt vmcnt(15)
	v_lshl_or_b32 v6, v84, 16, v68
	s_waitcnt vmcnt(14)
	v_lshl_or_b32 v7, v85, 16, v69
	global_store_dwordx4 v36, v[4:7], s[62:63] offset:256
	s_waitcnt vmcnt(14)
	s_nop 0
	v_lshl_or_b32 v4, v86, 16, v62
	s_waitcnt vmcnt(13)
	v_lshl_or_b32 v5, v87, 16, v63
	s_waitcnt vmcnt(12)
	v_lshl_or_b32 v6, v88, 16, v70
	s_waitcnt vmcnt(11)
	v_lshl_or_b32 v7, v89, 16, v71
	global_store_dwordx4 v36, v[4:7], s[62:63] offset:512
	s_waitcnt vmcnt(11)
	s_nop 0
	v_lshl_or_b32 v4, v90, 16, v64
	s_waitcnt vmcnt(10)
	v_lshl_or_b32 v5, v92, 16, v65
	s_waitcnt vmcnt(9)
	v_lshl_or_b32 v6, v93, 16, v72
	s_waitcnt vmcnt(8)
	v_lshl_or_b32 v7, v94, 16, v73
	global_store_dwordx4 v36, v[4:7], s[62:63] offset:768
	s_cbranch_vccnz .LBB0_810
; #define GAS __attribute__((address_space(1)))
; #define LAS __attribute__((address_space(3)))
; #define LDS_WAIT() asm volatile("s_waitcnt lgkmcnt(0)" ::: "memory")
; DI void hgrn_prep_job(const Frame& F, int job, int layer, LAS unsigned char* scr) {
;     ...
;     LDS_WAIT(); asm volatile("" ::: "memory");
;     const int r = lane & 15, g = lane >> 4;
; #pragma unroll
;     for (int mt = 0; mt < 2; ++mt)
; #pragma unroll
;         for (int kb = 0; kb < 4; ++kb) {
;             const LAS unsigned char* p = QL + (16 * mt + r) * 272 + (32 * kb + 4 * g) * 2;
;             const v2u lo = *(const LAS v2u*)p, hi = *(const LAS v2u*)(p + 32);
;             *(GAS v4u*)(hq + ((mt * 4 + kb) * 64 + lane) * 16) = (v4u){lo.x, lo.y, hi.x, hi.y};
;         }
;     f32x4 acc[2][2];
; #pragma unroll
;     for (int mt = 0; mt < 2; ++mt)
; #pragma unroll
;         for (int nt = 0; nt < 2; ++nt) acc[mt][nt] = (f32x4){0.f, 0.f, 0.f, 0.f};
; #pragma unroll
;     for (int ks = 0; ks < 4; ++ks) {
;         bf16x8 af[2], bfr[2];
; #pragma unroll
;         for (int mt = 0; mt < 2; ++mt) { af[mt] = *(const LAS bf16x8*)(QL + (16 * mt + r) * 272 + (32 * ks + 8 * g) * 2); bfr[mt] = *(const LAS bf16x8*)(KL + (16 * mt + r) * 272 + (32 * ks + 8 * g) * 2); }
; #pragma unroll
;         for (int mt = 0; mt < 2; ++mt)
; #pragma unroll
;             for (int nt = 0; nt < 2; ++nt) acc[mt][nt] = __builtin_amdgcn_mfma_f32_16x16x32_bf16(af[mt], bfr[nt], acc[mt][nt], 0, 0, 0);
;     }
;     LDS_WAIT(); asm volatile("" ::: "memory");
; #pragma unroll
;     for (int mt = 0; mt < 2; ++mt)
; #pragma unroll
;         for (int nt = 0; nt < 2; ++nt)
; #pragma unroll
;             for (int i = 0; i < 4; ++i) { const int t = 16 * mt + 4 * g + i, s = 16 * nt + r;
;                 *(LAS bf16*)(KL + t * 80 + s * 2) = (bf16)(pk2(s <= t ? acc[mt][nt][i] : 0.f, 0.f) & 0xffffu); }
;     LDS_WAIT(); asm volatile("" ::: "memory");
; #pragma unroll
;     for (int mt = 0; mt < 2; ++mt) {
;         const LAS unsigned char* p = KL + (16 * mt + r) * 80 + (4 * g) * 2;
;         const v2u lo = *(const LAS v2u*)p, hi = *(const LAS v2u*)(p + 32);
;         *(GAS v4u*)(ha + (mt * 64 + lane) * 16) = (v4u){lo.x, lo.y, hi.x, hi.y};
;     }
;     LDS_WAIT(); asm volatile("" ::: "memory");
	s_waitcnt lgkmcnt(0)
	v_add_u32_e32 v10, v50, v51
	ds_read2_b64 v[4:7], v10 offset1:4
	v_lshl_add_u64 v[8:9], v[0:1], 0, s[58:59]
	s_movk_i32 s0, 0x1000
	s_waitcnt lgkmcnt(0)
	global_store_dwordx4 v[8:9], v[4:7], off
	ds_read2_b64 v[4:7], v10 offset0:8 offset1:12
	s_waitcnt lgkmcnt(0)
	global_store_dwordx4 v[8:9], v[4:7], off offset:1024
	ds_read2_b64 v[4:7], v10 offset0:16 offset1:20
	s_waitcnt lgkmcnt(0)
	global_store_dwordx4 v[8:9], v[4:7], off offset:2048
	ds_read2_b64 v[4:7], v10 offset0:24 offset1:28
	v_add_u32_e32 v10, 0x1000, v10
	s_waitcnt lgkmcnt(0)
	global_store_dwordx4 v[8:9], v[4:7], off offset:3072
	ds_read2_b64 v[4:7], v10 offset0:32 offset1:36
	v_add_co_u32_e32 v8, vcc, s0, v8
	s_nop 1
	v_addc_co_u32_e32 v9, vcc, 0, v9, vcc
	s_waitcnt lgkmcnt(0)
	global_store_dwordx4 v[8:9], v[4:7], off
	ds_read2_b64 v[4:7], v10 offset0:40 offset1:44
	s_waitcnt lgkmcnt(0)
	global_store_dwordx4 v[8:9], v[4:7], off offset:1024
	ds_read2_b64 v[4:7], v10 offset0:48 offset1:52
	s_waitcnt lgkmcnt(0)
	global_store_dwordx4 v[8:9], v[4:7], off offset:2048
	ds_read2_b64 v[4:7], v10 offset0:56 offset1:60
	s_waitcnt lgkmcnt(0)
	global_store_dwordx4 v[8:9], v[4:7], off offset:3072
	ds_read_b128 v[4:7], v56
	ds_read_b128 v[8:11], v56 offset:8704
	ds_read_b128 v[12:15], v56 offset:4352
	ds_read_b128 v[16:19], v56 offset:13056
	s_waitcnt lgkmcnt(2)
	v_mfma_f32_16x16x32_bf16 v[4:7], v[4:7], v[8:11], 0
	s_waitcnt lgkmcnt(1)
	v_mfma_f32_16x16x32_bf16 v[8:11], v[12:15], v[8:11], 0
	s_waitcnt lgkmcnt(0)
	v_mfma_f32_16x16x32_bf16 v[12:15], v[12:15], v[16:19], 0
	ds_read_b128 v[16:19], v56 offset:64
	ds_read_b128 v[20:23], v56 offset:8768
	ds_read_b128 v[24:27], v56 offset:4416
	ds_read_b128 v[28:31], v56 offset:13120
	s_waitcnt lgkmcnt(2)
	v_mfma_f32_16x16x32_bf16 v[4:7], v[16:19], v[20:23], v[4:7]
	s_waitcnt lgkmcnt(1)
	v_mfma_f32_16x16x32_bf16 v[8:11], v[24:27], v[20:23], v[8:11]
	s_waitcnt lgkmcnt(0)
	v_mfma_f32_16x16x32_bf16 v[12:15], v[24:27], v[28:31], v[12:15]
	ds_read_b128 v[16:19], v56 offset:128
	ds_read_b128 v[20:23], v56 offset:8832
	ds_read_b128 v[24:27], v56 offset:4480
	ds_read_b128 v[28:31], v56 offset:13184
	s_waitcnt lgkmcnt(2)
	v_mfma_f32_16x16x32_bf16 v[4:7], v[16:19], v[20:23], v[4:7]
	s_waitcnt lgkmcnt(1)
	v_mfma_f32_16x16x32_bf16 v[8:11], v[24:27], v[20:23], v[8:11]
	s_waitcnt lgkmcnt(0)
	v_mfma_f32_16x16x32_bf16 v[12:15], v[24:27], v[28:31], v[12:15]
	ds_read_b128 v[16:19], v56 offset:192
	ds_read_b128 v[20:23], v56 offset:8896
	ds_read_b128 v[24:27], v56 offset:4544
	ds_read_b128 v[28:31], v56 offset:13248
	s_waitcnt lgkmcnt(0)
	s_waitcnt lgkmcnt(2)
	v_mfma_f32_16x16x32_bf16 v[4:7], v[16:19], v[20:23], v[4:7]
	v_add_u32_e32 v16, v52, v53
	s_waitcnt lgkmcnt(1)
	v_mfma_f32_16x16x32_bf16 v[8:11], v[24:27], v[20:23], v[8:11]
	s_waitcnt lgkmcnt(0)
	v_mfma_f32_16x16x32_bf16 v[12:15], v[24:27], v[28:31], v[12:15]
	s_nop 2
	v_cvt_pk_bf16_f32 v4, v4, s0
	v_cndmask_b32_e64 v4, v4, 0, s[40:41]
	ds_write_b16 v16, v4 offset:8704
	v_cvt_pk_bf16_f32 v4, v5, s0
	v_cndmask_b32_e64 v4, v4, 0, s[42:43]
	v_add_u32_e32 v5, v52, v54
	ds_write_b16 v5, v4 offset:8704
	v_cvt_pk_bf16_f32 v4, v6, s0
	v_cndmask_b32_e64 v4, v4, 0, s[44:45]
	ds_write_b16 v5, v4 offset:8784
	v_cvt_pk_bf16_f32 v4, v7, s0
	v_cndmask_b32_e64 v4, v4, 0, s[46:47]
	ds_write_b16 v5, v4 offset:8864
	v_add_u32_e32 v4, v55, v53
	v_add_u32_e32 v6, v55, v54
	v_cvt_pk_bf16_f32 v7, v8, s0
	ds_write_b16 v4, v97 offset:8704
	ds_write_b16 v6, v97 offset:8704
	ds_write_b16 v6, v97 offset:8784
	ds_write_b16 v6, v97 offset:8864
	ds_write_b16 v16, v7 offset:9984
	v_cvt_pk_bf16_f32 v7, v9, s0
	ds_write_b16 v5, v7 offset:9984
	v_cvt_pk_bf16_f32 v7, v10, s0
	ds_write_b16 v5, v7 offset:10064
	v_cvt_pk_bf16_f32 v7, v11, s0
	ds_write_b16 v5, v7 offset:10144
	v_cvt_pk_bf16_f32 v5, v12, s0
	v_cndmask_b32_e64 v5, v5, 0, s[40:41]
	ds_write_b16 v4, v5 offset:9984
	v_cvt_pk_bf16_f32 v4, v13, s0
	v_cndmask_b32_e64 v4, v4, 0, s[48:49]
	ds_write_b16 v6, v4 offset:9984
	v_cvt_pk_bf16_f32 v4, v14, s0
	v_cndmask_b32_e64 v4, v4, 0, s[50:51]
	ds_write_b16 v6, v4 offset:10064
	v_cvt_pk_bf16_f32 v4, v15, s0
	v_cndmask_b32_e64 v4, v4, 0, s[52:53]
	ds_write_b16 v6, v4 offset:10144
	s_waitcnt lgkmcnt(0)
	v_add_u32_e32 v10, 0x2000, v57
	ds_read2_b64 v[4:7], v10 offset0:64 offset1:68
	s_lshl_b64 s[0:1], s[54:55], 11
	v_lshl_add_u64 v[8:9], v[2:3], 0, s[0:1]
	v_readlane_b32 s0, v253, 34
	s_add_i32 s30, s30, s0
	s_waitcnt lgkmcnt(0)
	global_store_dwordx4 v[8:9], v[4:7], off
	ds_read2_b64 v[4:7], v10 offset0:224 offset1:228
	s_cmpk_gt_i32 s30, 0x5ff
	v_readlane_b32 s1, v253, 35
	s_waitcnt lgkmcnt(0)
	global_store_dwordx4 v[8:9], v[4:7], off offset:1024
	s_waitcnt lgkmcnt(0)
	s_cbranch_scc0 .LBB0_809
